# k28: k26 + more de-serialized glue: second d_skip prefetch in S5 item, sample out-projection and GLU epilogues issue all loads before the first wait, P0 cache-logf copy two elements per round, attenti
# speedup vs baseline: 1.0194x; 1.0010x over previous
; #define LFS WSP(float, WS_LFS)
; __global__ void __launch_bounds__(NTHR, 2) hymba_fwd(Params P) {
;     ...
;         for (int i = gt; i < NB * PAST * NH; i += NGT) { const int b = i / (PAST * NH), r = i % (PAST * NH); LFS[(size_t)b * SKV * NH + r] = P.cache_logf[i]; }
.LBB0_75:
	v_add_u32_e32 v9, s10, v2
	v_cmp_gt_i32_e64 s[6:7], s3, v9
	v_cmp_ge_i32_e64 s[6:7], s3, v9
	v_lshlrev_b32_e32 v4, 2, v2
	global_load_dword v1, v4, s[44:45]
	s_mov_b64 s[12:13], exec
	s_and_b64 exec, exec, s[6:7]
	v_lshlrev_b32_e32 v5, 2, v9
	global_load_dword v8, v5, s[44:45]
	s_mov_b64 exec, s[12:13]
	v_ashrrev_i32_e32 v7, 31, v2
	v_lshrrev_b32_e32 v7, 18, v7
	v_add_u32_e32 v7, v2, v7
	v_ashrrev_i32_e32 v7, 14, v7
	v_mul_i32_i24_e32 v6, 0x4000, v7
	v_sub_u32_e32 v6, v2, v6
	v_mul_i32_i24_e32 v7, 0x840, v7
	v_lshl_add_u32 v6, v7, 3, v6
	v_lshlrev_b32_e32 v6, 2, v6
	v_ashrrev_i32_e32 v11, 31, v9
	v_lshrrev_b32_e32 v11, 18, v11
	v_add_u32_e32 v11, v9, v11
	v_ashrrev_i32_e32 v11, 14, v11
	v_mul_i32_i24_e32 v10, 0x4000, v11
	v_sub_u32_e32 v10, v9, v10
	v_mul_i32_i24_e32 v11, 0x840, v11
	v_lshl_add_u32 v10, v11, 3, v10
	v_lshlrev_b32_e32 v10, 2, v10
	s_waitcnt vmcnt(1)
	global_store_dword v6, v1, s[42:43]
	s_and_b64 exec, exec, s[6:7]
	s_waitcnt vmcnt(1)
	global_store_dword v10, v8, s[42:43]
	v_add_u32_e32 v2, s10, v9
	v_cmp_ge_i32_e32 vcc, s3, v2
	s_and_b64 exec, exec, vcc
	s_cbranch_execnz .LBB0_75

; __host__ __device__ __forceinline__ size_t ux_off(int m, int ch) { return ((size_t)((ch >> 4) * UXROWS + (m >> 4)) * UXR + (m & 15)) * 16 + (ch & 15); }
; __device__ __forceinline__ f32x2 cmul(f32x2 a, f32x2 b) { return (f32x2){a.x * b.x - a.y * b.y, a.x * b.y + a.y * b.x}; }
; __global__ void __launch_bounds__(NTHR, 2) hymba_fwd(Params P) {
;     ...
;         for (int i = tid; i < 1024; i += NTHR) { const int t = i >> 4, p = i & 15, s = b * 64 + t; US[i] = bf2f(UX[ux_off(PT + s, g * 16 + p)]);
;             CR[(i >> 6) * 65 + (i & 63)] = P.c_re[g * 1024 + i]; CI[(i >> 6) * 65 + (i & 63)] = P.c_im[g * 1024 + i]; }
;         __syncthreads();
;         { const int n = lane; f32x2 bb[16];
; #pragma unroll
;           for (int p = 0; p < 16; ++p) bb[p] = BBAR[(g * 64 + n) * 16 + p];
; #pragma unroll
;           for (int tt = 0; tt < 8; ++tt) { const int t = wave * 8 + tt; f32x2 bu = {0.f, 0.f};
; #pragma unroll
;               for (int p = 0; p < 16; ++p) { const float uu = US[t * 16 + p]; bu.x += bb[p].x * uu; bu.y += bb[p].y * uu; }
;               XS[t * 65 + n] = bu; } }
;         __syncthreads();
;         if (wave == 0) { const int n = lane; f32x2 xst = {P.st_re[(b * NG + g) * 64 + n], P.st_im[(b * NG + g) * 64 + n]}; const f32x2 ab = ABAR[g * 64 + n];
; #pragma unroll 8
;             for (int t = 0; t < 64; ++t) { const f32x2 bu = XS[t * 65 + n]; const f32x2 ax = cmul(ab, xst); xst = (f32x2){ax.x + bu.x, ax.y + bu.y}; XS[t * 65 + n] = xst; }
;             out[O_RS + (b * NG + g) * 64 + n] = xst.x; out[O_IS + (b * NG + g) * 64 + n] = xst.y; }
;         __syncthreads();
;         { const int t = tid >> 3, pp = tid & 7;
; #pragma unroll
;           for (int e = 0; e < 2; ++e) { const int p = pp + 8 * e; float y = P.d_skip[g * 16 + p] * US[t * 16 + p];
.LBB0_622:
	v_add_u32_e32 v62, 0x200, v7
	v_ashrrev_i32_e32 v60, 4, v7
	v_add_u32_e32 v61, s50, v60
	v_ashrrev_i32_e32 v61, 4, v61
	v_add_u32_e32 v61, s51, v61
	v_and_b32_e32 v32, 15, v60
	v_mad_i64_i32 v[64:65], s[52:53], v61, 24, v[32:33]
	v_lshlrev_b64 v[64:65], 5, v[64:65]
	v_lshl_add_u64 v[64:65], v[0:1], 0, v[64:65]
	global_load_ushort v70, v[64:65], off
	v_ashrrev_i32_e32 v60, 4, v62
	v_add_u32_e32 v61, s50, v60
	v_ashrrev_i32_e32 v61, 4, v61
	v_add_u32_e32 v61, s51, v61
	v_and_b32_e32 v32, 15, v60
	v_mad_i64_i32 v[66:67], s[52:53], v61, 24, v[32:33]
	v_lshlrev_b64 v[66:67], 5, v[66:67]
	v_lshl_add_u64 v[66:67], v[0:1], 0, v[66:67]
	global_load_ushort v71, v[66:67], off
	global_load_dword v72, v[2:3], off
	global_load_dword v73, v[2:3], off offset:2048
	global_load_dword v74, v[4:5], off
	global_load_dword v75, v[4:5], off offset:2048
	v_readlane_b32 s52, v255, 10
	v_readlane_b32 s53, v255, 11
	v_lshlrev_b32_e32 v78, 4, v34
	v_or_b32_e32 v78, s45, v78
	v_lshlrev_b32_e32 v78, 3, v78
	global_load_dwordx4 v[80:83], v78, s[52:53]
	global_load_dwordx4 v[84:87], v78, s[52:53] offset:16
	global_load_dwordx4 v[88:91], v78, s[52:53] offset:32
	global_load_dwordx4 v[92:95], v78, s[52:53] offset:48
	global_load_dwordx4 v[96:99], v78, s[52:53] offset:64
	global_load_dwordx4 v[100:103], v78, s[52:53] offset:80
	global_load_dwordx4 v[104:107], v78, s[52:53] offset:96
	global_load_dwordx4 v[108:111], v78, s[52:53] offset:112
	v_and_b32_e32 v77, 7, v35
	s_lshl_b32 s52, s35, 4
	v_or_b32_e32 v77, s52, v77
	v_lshlrev_b32_e32 v77, 2, v77
	global_load_dword v76, v77, s[82:83]
	global_load_dword v116, v77, s[82:83] offset:32
	s_lshl_b32 s52, s34, 6
	v_or_b32_e32 v79, s52, v34
	v_lshlrev_b32_e32 v79, 2, v79
	global_load_dword v112, v79, s[46:47]
	global_load_dword v113, v79, s[48:49]
	v_readlane_b32 s52, v255, 6
	v_readlane_b32 s53, v255, 7
	v_lshlrev_b32_e32 v79, 3, v34
	v_lshl_or_b32 v79, s35, 9, v79
	s_nop 1
	global_load_dwordx2 v[114:115], v79, s[52:53]
	s_movk_i32 s52, 0x41
	v_ashrrev_i32_e32 v60, 6, v7
	v_mad_u32_u24 v60, v60, s52, v34
	v_lshlrev_b32_e32 v60, 2, v60
	v_ashrrev_i32_e32 v61, 6, v62
	v_mad_u32_u24 v61, v61, s52, v34
	v_lshlrev_b32_e32 v61, 2, v61
	s_waitcnt vmcnt(18)
	v_lshlrev_b32_e32 v70, 16, v70
	ds_write_b32 v6, v70
	s_waitcnt vmcnt(17)
	v_lshlrev_b32_e32 v71, 16, v71
	ds_write_b32 v6, v71 offset:2048
	s_waitcnt vmcnt(16)
	ds_write_b32 v60, v72 offset:37376
	s_waitcnt vmcnt(15)
	ds_write_b32 v61, v73 offset:37376
	s_waitcnt vmcnt(14)
	ds_write_b32 v60, v74 offset:41536
	s_waitcnt vmcnt(13)
	ds_write_b32 v61, v75 offset:41536
	s_or_b64 exec, exec, s[12:13]
	v_mov_b32_e32 v0, s45
.LBB0_624:
	s_or_b64 exec, exec, s[10:11]
	v_readlane_b32 s10, v255, 10
	v_lshl_or_b32 v32, v34, 4, v0
	v_readlane_b32 s11, v255, 11
	s_waitcnt lgkmcnt(0)
	s_barrier
	v_lshl_add_u64 v[16:17], v[32:33], 3, s[10:11]
	s_waitcnt vmcnt(5)
	v_mov_b64_e32 v[12:13], v[80:81]
	v_mov_b64_e32 v[14:15], v[82:83]
	v_mov_b64_e32 v[8:9], v[84:85]
	v_mov_b64_e32 v[10:11], v[86:87]
	v_mov_b64_e32 v[4:5], v[88:89]
	v_mov_b64_e32 v[6:7], v[90:91]
	v_mov_b64_e32 v[0:1], v[92:93]
	v_mov_b64_e32 v[2:3], v[94:95]
	v_mov_b64_e32 v[28:29], v[96:97]
	v_mov_b64_e32 v[30:31], v[98:99]
	v_mov_b64_e32 v[24:25], v[100:101]
	v_mov_b64_e32 v[26:27], v[102:103]
	v_mov_b64_e32 v[20:21], v[104:105]
	v_mov_b64_e32 v[22:23], v[106:107]
	s_nop 0
	v_mov_b64_e32 v[16:17], v[108:109]
	v_mov_b64_e32 v[18:19], v[110:111]
	s_ashr_i32 s10, s44, 3
	s_and_b32 s11, s10, -8
	s_lshl_b32 s12, s11, 6
	s_add_i32 s12, s12, 0
	v_mov_b32_e32 v55, s12
	ds_read_b128 v[36:39], v55 offset:33280
	ds_read_b128 v[40:43], v55 offset:33296
	ds_read_b128 v[44:47], v55 offset:33312
	ds_read_b128 v[48:51], v55 offset:33328
	v_lshl_add_u32 v32, v34, 3, 0
	s_waitcnt lgkmcnt(3)
	v_mov_b32_e32 v52, v39
	s_waitcnt lgkmcnt(2)
	v_mov_b32_e32 v54, v43
	s_mulk_i32 s11, 0x208
	v_add_u32_e32 v57, s11, v32
	s_waitcnt lgkmcnt(1)
	v_mov_b32_e32 v56, v47
	s_waitcnt lgkmcnt(0)
	v_mov_b32_e32 v58, v51
	s_or_b32 s10, s10, 7
	s_lshl_b32 s11, s10, 6
	s_mulk_i32 s10, 0x208
	s_add_i32 s11, s11, 0
	s_cmp_lt_u32 s44, 64
	s_waitcnt vmcnt(7)
	v_pk_fma_f32 v[60:61], v[36:37], v[12:13], 0 op_sel_hi:[0,1,0]
	v_pk_fma_f32 v[36:37], v[36:37], v[14:15], v[60:61] op_sel:[1,0,0]
	s_waitcnt vmcnt(6)
	v_pk_fma_f32 v[36:37], v[38:39], v[8:9], v[36:37] op_sel_hi:[0,1,1]
	v_pk_fma_f32 v[36:37], v[52:53], v[10:11], v[36:37] op_sel_hi:[0,1,1]
	s_waitcnt vmcnt(5)
	v_pk_fma_f32 v[36:37], v[40:41], v[4:5], v[36:37] op_sel_hi:[0,1,1]
	v_pk_fma_f32 v[36:37], v[40:41], v[6:7], v[36:37] op_sel:[1,0,0]
	s_waitcnt vmcnt(4)
	v_pk_fma_f32 v[36:37], v[42:43], v[0:1], v[36:37] op_sel_hi:[0,1,1]
	v_pk_fma_f32 v[36:37], v[54:55], v[2:3], v[36:37] op_sel_hi:[0,1,1]
	s_waitcnt vmcnt(3)
	v_pk_fma_f32 v[36:37], v[44:45], v[28:29], v[36:37] op_sel_hi:[0,1,1]
	v_pk_fma_f32 v[36:37], v[44:45], v[30:31], v[36:37] op_sel:[1,0,0]
	s_waitcnt vmcnt(2)
	v_pk_fma_f32 v[36:37], v[46:47], v[24:25], v[36:37] op_sel_hi:[0,1,1]
	v_pk_fma_f32 v[36:37], v[56:57], v[26:27], v[36:37] op_sel_hi:[0,1,1]
	s_waitcnt vmcnt(1)
	v_pk_fma_f32 v[36:37], v[48:49], v[20:21], v[36:37] op_sel_hi:[0,1,1]
	v_pk_fma_f32 v[36:37], v[48:49], v[22:23], v[36:37] op_sel:[1,0,0]
	s_waitcnt vmcnt(0)
	v_pk_fma_f32 v[36:37], v[50:51], v[16:17], v[36:37] op_sel_hi:[0,1,1]
	v_pk_fma_f32 v[36:37], v[58:59], v[18:19], v[36:37] op_sel_hi:[0,1,1]
	ds_write_b64 v57, v[36:37]
	ds_read_b128 v[36:39], v55 offset:33344
	ds_read_b128 v[40:43], v55 offset:33360
	ds_read_b128 v[44:47], v55 offset:33376
	ds_read_b128 v[48:51], v55 offset:33392
	s_waitcnt lgkmcnt(2)
; __global__ void __launch_bounds__(NTHR, 2) hymba_fwd(Params P) {
;     ...
;           for (int tt = 0; tt < 8; ++tt) { const int t = wave * 8 + tt; f32x2 bu = {0.f, 0.f};
; #pragma unroll
;               for (int p = 0; p < 16; ++p) { const float uu = US[t * 16 + p]; bu.x += bb[p].x * uu; bu.y += bb[p].y * uu; }
;               XS[t * 65 + n] = bu; } }
	v_mov_b32_e32 v56, v43
	v_pk_fma_f32 v[52:53], v[36:37], v[12:13], 0 op_sel_hi:[0,1,0]
	v_pk_fma_f32 v[36:37], v[36:37], v[14:15], v[52:53] op_sel:[1,0,0]
	v_mov_b32_e32 v54, v39
	v_pk_fma_f32 v[36:37], v[38:39], v[8:9], v[36:37] op_sel_hi:[0,1,1]
	v_pk_fma_f32 v[36:37], v[54:55], v[10:11], v[36:37] op_sel_hi:[0,1,1]
	v_pk_fma_f32 v[36:37], v[40:41], v[4:5], v[36:37] op_sel_hi:[0,1,1]
	v_pk_fma_f32 v[36:37], v[40:41], v[6:7], v[36:37] op_sel:[1,0,0]
	s_waitcnt lgkmcnt(1)
	v_mov_b32_e32 v58, v47
	v_pk_fma_f32 v[36:37], v[42:43], v[0:1], v[36:37] op_sel_hi:[0,1,1]
	v_pk_fma_f32 v[36:37], v[56:57], v[2:3], v[36:37] op_sel_hi:[0,1,1]
	v_pk_fma_f32 v[36:37], v[44:45], v[28:29], v[36:37] op_sel_hi:[0,1,1]
	v_pk_fma_f32 v[36:37], v[44:45], v[30:31], v[36:37] op_sel:[1,0,0]
	s_waitcnt lgkmcnt(0)
	v_mov_b32_e32 v60, v51
	v_pk_fma_f32 v[36:37], v[46:47], v[24:25], v[36:37] op_sel_hi:[0,1,1]
	v_pk_fma_f32 v[36:37], v[58:59], v[26:27], v[36:37] op_sel_hi:[0,1,1]
	v_pk_fma_f32 v[36:37], v[48:49], v[20:21], v[36:37] op_sel_hi:[0,1,1]
	v_pk_fma_f32 v[36:37], v[48:49], v[22:23], v[36:37] op_sel:[1,0,0]
	s_nop 0
	v_pk_fma_f32 v[36:37], v[50:51], v[16:17], v[36:37] op_sel_hi:[0,1,1]
	v_pk_fma_f32 v[36:37], v[60:61], v[18:19], v[36:37] op_sel_hi:[0,1,1]
	ds_write_b64 v57, v[36:37] offset:520
	ds_read_b128 v[36:39], v55 offset:33408
	ds_read_b128 v[40:43], v55 offset:33424
	ds_read_b128 v[44:47], v55 offset:33440
	ds_read_b128 v[48:51], v55 offset:33456
	s_waitcnt lgkmcnt(2)
	v_mov_b32_e32 v56, v43
	v_pk_fma_f32 v[52:53], v[36:37], v[12:13], 0 op_sel_hi:[0,1,0]
	v_pk_fma_f32 v[36:37], v[36:37], v[14:15], v[52:53] op_sel:[1,0,0]
	v_mov_b32_e32 v54, v39
	v_pk_fma_f32 v[36:37], v[38:39], v[8:9], v[36:37] op_sel_hi:[0,1,1]
	v_pk_fma_f32 v[36:37], v[54:55], v[10:11], v[36:37] op_sel_hi:[0,1,1]
	v_pk_fma_f32 v[36:37], v[40:41], v[4:5], v[36:37] op_sel_hi:[0,1,1]
	v_pk_fma_f32 v[36:37], v[40:41], v[6:7], v[36:37] op_sel:[1,0,0]
	s_waitcnt lgkmcnt(1)
	v_mov_b32_e32 v58, v47
	v_pk_fma_f32 v[36:37], v[42:43], v[0:1], v[36:37] op_sel_hi:[0,1,1]
	v_pk_fma_f32 v[36:37], v[56:57], v[2:3], v[36:37] op_sel_hi:[0,1,1]
	v_pk_fma_f32 v[36:37], v[44:45], v[28:29], v[36:37] op_sel_hi:[0,1,1]
	v_pk_fma_f32 v[36:37], v[44:45], v[30:31], v[36:37] op_sel:[1,0,0]
	s_waitcnt lgkmcnt(0)
	v_mov_b32_e32 v60, v51
	v_pk_fma_f32 v[36:37], v[46:47], v[24:25], v[36:37] op_sel_hi:[0,1,1]
	v_pk_fma_f32 v[36:37], v[58:59], v[26:27], v[36:37] op_sel_hi:[0,1,1]
	v_pk_fma_f32 v[36:37], v[48:49], v[20:21], v[36:37] op_sel_hi:[0,1,1]
	v_pk_fma_f32 v[36:37], v[48:49], v[22:23], v[36:37] op_sel:[1,0,0]
	s_nop 0
	v_pk_fma_f32 v[36:37], v[50:51], v[16:17], v[36:37] op_sel_hi:[0,1,1]
	v_pk_fma_f32 v[36:37], v[60:61], v[18:19], v[36:37] op_sel_hi:[0,1,1]
	ds_write_b64 v57, v[36:37] offset:1040
	ds_read_b128 v[36:39], v55 offset:33472
	ds_read_b128 v[40:43], v55 offset:33488
	ds_read_b128 v[44:47], v55 offset:33504
	ds_read_b128 v[48:51], v55 offset:33520
	s_waitcnt lgkmcnt(2)
	v_mov_b32_e32 v56, v43
	v_pk_fma_f32 v[52:53], v[36:37], v[12:13], 0 op_sel_hi:[0,1,0]
	v_pk_fma_f32 v[36:37], v[36:37], v[14:15], v[52:53] op_sel:[1,0,0]
	v_mov_b32_e32 v54, v39
	v_pk_fma_f32 v[36:37], v[38:39], v[8:9], v[36:37] op_sel_hi:[0,1,1]
	v_pk_fma_f32 v[36:37], v[54:55], v[10:11], v[36:37] op_sel_hi:[0,1,1]
	v_pk_fma_f32 v[36:37], v[40:41], v[4:5], v[36:37] op_sel_hi:[0,1,1]
	v_pk_fma_f32 v[36:37], v[40:41], v[6:7], v[36:37] op_sel:[1,0,0]
	s_waitcnt lgkmcnt(1)
	v_mov_b32_e32 v58, v47
	v_pk_fma_f32 v[36:37], v[42:43], v[0:1], v[36:37] op_sel_hi:[0,1,1]
	v_pk_fma_f32 v[36:37], v[56:57], v[2:3], v[36:37] op_sel_hi:[0,1,1]
	v_pk_fma_f32 v[36:37], v[44:45], v[28:29], v[36:37] op_sel_hi:[0,1,1]
	v_pk_fma_f32 v[36:37], v[44:45], v[30:31], v[36:37] op_sel:[1,0,0]
	s_waitcnt lgkmcnt(0)
	v_mov_b32_e32 v60, v51
	v_pk_fma_f32 v[36:37], v[46:47], v[24:25], v[36:37] op_sel_hi:[0,1,1]
	v_pk_fma_f32 v[36:37], v[58:59], v[26:27], v[36:37] op_sel_hi:[0,1,1]
	v_pk_fma_f32 v[36:37], v[48:49], v[20:21], v[36:37] op_sel_hi:[0,1,1]
	v_pk_fma_f32 v[36:37], v[48:49], v[22:23], v[36:37] op_sel:[1,0,0]
	s_nop 0
	v_pk_fma_f32 v[36:37], v[50:51], v[16:17], v[36:37] op_sel_hi:[0,1,1]
	v_pk_fma_f32 v[36:37], v[60:61], v[18:19], v[36:37] op_sel_hi:[0,1,1]
	ds_write_b64 v57, v[36:37] offset:1560
	ds_read_b128 v[36:39], v55 offset:33536
	ds_read_b128 v[40:43], v55 offset:33552
	ds_read_b128 v[44:47], v55 offset:33568
	ds_read_b128 v[48:51], v55 offset:33584
	s_waitcnt lgkmcnt(2)
	v_mov_b32_e32 v56, v43
	v_pk_fma_f32 v[52:53], v[36:37], v[12:13], 0 op_sel_hi:[0,1,0]
	v_pk_fma_f32 v[36:37], v[36:37], v[14:15], v[52:53] op_sel:[1,0,0]
	v_mov_b32_e32 v54, v39
	v_pk_fma_f32 v[36:37], v[38:39], v[8:9], v[36:37] op_sel_hi:[0,1,1]
	v_pk_fma_f32 v[36:37], v[54:55], v[10:11], v[36:37] op_sel_hi:[0,1,1]
	v_pk_fma_f32 v[36:37], v[40:41], v[4:5], v[36:37] op_sel_hi:[0,1,1]
	v_pk_fma_f32 v[36:37], v[40:41], v[6:7], v[36:37] op_sel:[1,0,0]
	s_waitcnt lgkmcnt(1)
	v_mov_b32_e32 v58, v47
	v_pk_fma_f32 v[36:37], v[42:43], v[0:1], v[36:37] op_sel_hi:[0,1,1]
	v_pk_fma_f32 v[36:37], v[56:57], v[2:3], v[36:37] op_sel_hi:[0,1,1]
	v_pk_fma_f32 v[36:37], v[44:45], v[28:29], v[36:37] op_sel_hi:[0,1,1]
	v_pk_fma_f32 v[36:37], v[44:45], v[30:31], v[36:37] op_sel:[1,0,0]
	s_waitcnt lgkmcnt(0)
; __global__ void __launch_bounds__(NTHR, 2) hymba_fwd(Params P) {
;     ...
;           for (int tt = 0; tt < 8; ++tt) { const int t = wave * 8 + tt; f32x2 bu = {0.f, 0.f};
; #pragma unroll
;               for (int p = 0; p < 16; ++p) { const float uu = US[t * 16 + p]; bu.x += bb[p].x * uu; bu.y += bb[p].y * uu; }
;               XS[t * 65 + n] = bu; } }
;         __syncthreads();
;         if (wave == 0) { const int n = lane; f32x2 xst = {P.st_re[(b * NG + g) * 64 + n], P.st_im[(b * NG + g) * 64 + n]}; const f32x2 ab = ABAR[g * 64 + n];
	v_mov_b32_e32 v60, v51
	v_pk_fma_f32 v[36:37], v[46:47], v[24:25], v[36:37] op_sel_hi:[0,1,1]
	v_pk_fma_f32 v[36:37], v[58:59], v[26:27], v[36:37] op_sel_hi:[0,1,1]
	v_pk_fma_f32 v[36:37], v[48:49], v[20:21], v[36:37] op_sel_hi:[0,1,1]
	v_pk_fma_f32 v[36:37], v[48:49], v[22:23], v[36:37] op_sel:[1,0,0]
	v_add_u32_e32 v59, s10, v32
	v_pk_fma_f32 v[36:37], v[50:51], v[16:17], v[36:37] op_sel_hi:[0,1,1]
	v_pk_fma_f32 v[36:37], v[60:61], v[18:19], v[36:37] op_sel_hi:[0,1,1]
	ds_write_b64 v57, v[36:37] offset:2080
	ds_read_b128 v[36:39], v55 offset:33600
	ds_read_b128 v[40:43], v55 offset:33616
	ds_read_b128 v[44:47], v55 offset:33632
	ds_read_b128 v[48:51], v55 offset:33648
	s_waitcnt lgkmcnt(2)
	v_mov_b32_e32 v56, v43
	v_pk_fma_f32 v[52:53], v[36:37], v[12:13], 0 op_sel_hi:[0,1,0]
	v_pk_fma_f32 v[36:37], v[36:37], v[14:15], v[52:53] op_sel:[1,0,0]
	v_mov_b32_e32 v54, v39
	v_pk_fma_f32 v[36:37], v[38:39], v[8:9], v[36:37] op_sel_hi:[0,1,1]
	v_pk_fma_f32 v[36:37], v[54:55], v[10:11], v[36:37] op_sel_hi:[0,1,1]
	v_pk_fma_f32 v[36:37], v[40:41], v[4:5], v[36:37] op_sel_hi:[0,1,1]
	v_pk_fma_f32 v[36:37], v[40:41], v[6:7], v[36:37] op_sel:[1,0,0]
	s_waitcnt lgkmcnt(1)
	v_mov_b32_e32 v58, v47
	v_pk_fma_f32 v[36:37], v[42:43], v[0:1], v[36:37] op_sel_hi:[0,1,1]
	v_pk_fma_f32 v[36:37], v[56:57], v[2:3], v[36:37] op_sel_hi:[0,1,1]
	v_pk_fma_f32 v[36:37], v[44:45], v[28:29], v[36:37] op_sel_hi:[0,1,1]
	v_pk_fma_f32 v[36:37], v[44:45], v[30:31], v[36:37] op_sel:[1,0,0]
	s_waitcnt lgkmcnt(0)
	v_mov_b32_e32 v60, v51
	v_pk_fma_f32 v[36:37], v[46:47], v[24:25], v[36:37] op_sel_hi:[0,1,1]
	v_pk_fma_f32 v[36:37], v[58:59], v[26:27], v[36:37] op_sel_hi:[0,1,1]
	v_pk_fma_f32 v[36:37], v[48:49], v[20:21], v[36:37] op_sel_hi:[0,1,1]
	v_pk_fma_f32 v[36:37], v[48:49], v[22:23], v[36:37] op_sel:[1,0,0]
	s_nop 0
	v_pk_fma_f32 v[36:37], v[50:51], v[16:17], v[36:37] op_sel_hi:[0,1,1]
	v_pk_fma_f32 v[36:37], v[60:61], v[18:19], v[36:37] op_sel_hi:[0,1,1]
	ds_write_b64 v57, v[36:37] offset:2600
	ds_read_b128 v[36:39], v55 offset:33664
	ds_read_b128 v[40:43], v55 offset:33680
	ds_read_b128 v[44:47], v55 offset:33696
	ds_read_b128 v[48:51], v55 offset:33712
	v_mov_b32_e32 v61, s11
	s_waitcnt lgkmcnt(2)
	v_mov_b32_e32 v56, v43
	v_pk_fma_f32 v[52:53], v[36:37], v[12:13], 0 op_sel_hi:[0,1,0]
	v_pk_fma_f32 v[36:37], v[36:37], v[14:15], v[52:53] op_sel:[1,0,0]
	v_mov_b32_e32 v54, v39
	v_pk_fma_f32 v[36:37], v[38:39], v[8:9], v[36:37] op_sel_hi:[0,1,1]
	v_pk_fma_f32 v[36:37], v[54:55], v[10:11], v[36:37] op_sel_hi:[0,1,1]
	v_pk_fma_f32 v[36:37], v[40:41], v[4:5], v[36:37] op_sel_hi:[0,1,1]
	v_pk_fma_f32 v[36:37], v[40:41], v[6:7], v[36:37] op_sel:[1,0,0]
	s_waitcnt lgkmcnt(1)
	v_mov_b32_e32 v58, v47
	v_pk_fma_f32 v[36:37], v[42:43], v[0:1], v[36:37] op_sel_hi:[0,1,1]
	v_pk_fma_f32 v[36:37], v[56:57], v[2:3], v[36:37] op_sel_hi:[0,1,1]
	v_pk_fma_f32 v[36:37], v[44:45], v[28:29], v[36:37] op_sel_hi:[0,1,1]
	v_pk_fma_f32 v[36:37], v[44:45], v[30:31], v[36:37] op_sel:[1,0,0]
	s_waitcnt lgkmcnt(0)
	v_mov_b32_e32 v60, v51
	v_pk_fma_f32 v[36:37], v[46:47], v[24:25], v[36:37] op_sel_hi:[0,1,1]
	v_pk_fma_f32 v[36:37], v[58:59], v[26:27], v[36:37] op_sel_hi:[0,1,1]
	v_pk_fma_f32 v[36:37], v[48:49], v[20:21], v[36:37] op_sel_hi:[0,1,1]
	v_pk_fma_f32 v[36:37], v[48:49], v[22:23], v[36:37] op_sel:[1,0,0]
	s_nop 0
	v_pk_fma_f32 v[36:37], v[50:51], v[16:17], v[36:37] op_sel_hi:[0,1,1]
	v_pk_fma_f32 v[36:37], v[60:61], v[18:19], v[36:37] op_sel_hi:[0,1,1]
	ds_write_b64 v57, v[36:37] offset:3120
	ds_read_b128 v[36:39], v61 offset:33280
	ds_read_b128 v[40:43], v61 offset:33296
	ds_read_b128 v[44:47], v61 offset:33312
	ds_read_b128 v[48:51], v61 offset:33328
	s_waitcnt lgkmcnt(2)
	v_mov_b32_e32 v54, v43
	v_pk_fma_f32 v[12:13], v[36:37], v[12:13], 0 op_sel_hi:[0,1,0]
	v_pk_fma_f32 v[12:13], v[36:37], v[14:15], v[12:13] op_sel:[1,0,0]
	v_mov_b32_e32 v52, v39
	v_pk_fma_f32 v[8:9], v[38:39], v[8:9], v[12:13] op_sel_hi:[0,1,1]
	v_pk_fma_f32 v[8:9], v[52:53], v[10:11], v[8:9] op_sel_hi:[0,1,1]
	v_pk_fma_f32 v[4:5], v[40:41], v[4:5], v[8:9] op_sel_hi:[0,1,1]
	v_pk_fma_f32 v[4:5], v[40:41], v[6:7], v[4:5] op_sel:[1,0,0]
	s_waitcnt lgkmcnt(1)
	v_mov_b32_e32 v56, v47
	v_pk_fma_f32 v[0:1], v[42:43], v[0:1], v[4:5] op_sel_hi:[0,1,1]
	v_pk_fma_f32 v[0:1], v[54:55], v[2:3], v[0:1] op_sel_hi:[0,1,1]
	v_pk_fma_f32 v[0:1], v[44:45], v[28:29], v[0:1] op_sel_hi:[0,1,1]
	v_pk_fma_f32 v[0:1], v[44:45], v[30:31], v[0:1] op_sel:[1,0,0]
	s_waitcnt lgkmcnt(0)
	v_mov_b32_e32 v58, v51
	v_pk_fma_f32 v[0:1], v[46:47], v[24:25], v[0:1] op_sel_hi:[0,1,1]
	v_pk_fma_f32 v[0:1], v[56:57], v[26:27], v[0:1] op_sel_hi:[0,1,1]
	v_pk_fma_f32 v[0:1], v[48:49], v[20:21], v[0:1] op_sel_hi:[0,1,1]
	v_pk_fma_f32 v[0:1], v[48:49], v[22:23], v[0:1] op_sel:[1,0,0]
	s_nop 0
	v_pk_fma_f32 v[0:1], v[50:51], v[16:17], v[0:1] op_sel_hi:[0,1,1]
	v_pk_fma_f32 v[0:1], v[58:59], v[18:19], v[0:1] op_sel_hi:[0,1,1]
	ds_write_b64 v59, v[0:1]
	s_waitcnt lgkmcnt(0)
	s_barrier
	s_cbranch_scc0 .LBB0_628
	s_lshl_b32 s10, s34, 6
	v_or_b32_e32 v0, s10, v34
	v_ashrrev_i32_e32 v1, 31, v0
	v_lshlrev_b64 v[0:1], 2, v[0:1]
	v_lshl_add_u64 v[2:3], s[46:47], 0, v[0:1]
	v_lshl_add_u64 v[0:1], s[48:49], 0, v[0:1]
	s_waitcnt vmcnt(0)
	v_mov_b32_e32 v2, v112
	v_readlane_b32 s12, v255, 6
	v_mov_b32_e32 v3, v113
	v_lshlrev_b32_e32 v0, 3, v34
	v_lshl_or_b32 v0, s35, 9, v0
	v_readlane_b32 s13, v255, 7
	s_mov_b32 s11, 0
	s_nop 3
	v_mov_b64_e32 v[0:1], v[114:115]

; __device__ __forceinline__ unsigned f2bf(float f) { unsigned u = __builtin_bit_cast(unsigned, f); return (u + 0x7fffu + ((u >> 16) & 1u)) >> 16; }
; __device__ __forceinline__ float gelu_tanh(float x) { const float z = 0.7978845608028654f * (x + 0.044715f * x * x * x); return x * __builtin_amdgcn_rcpf(1.f + __expf(-2.f * z)); }
; __global__ void __launch_bounds__(NTHR, 2) hymba_fwd(Params P) {
;     ...
;           for (int e = 0; e < 2; ++e) { const int p = pp + 8 * e; float y = P.d_skip[g * 16 + p] * US[t * 16 + p];
; #pragma unroll 8
;               for (int n = 0; n < 64; ++n) { const f32x2 xv = XS[t * 65 + n]; y += CR[p * 65 + n] * xv.x - CI[p * 65 + n] * xv.y; }
;               YSS[(size_t)(b * 64 + t) * 512 + g * 16 + p] = (bf16_t)f2bf(gelu_tanh(y)); } }
.LBB0_629:
	v_add_u32_e32 v7, s11, v5
	v_add_u32_e32 v32, 0x1040, v7
	v_add_u32_e32 v36, 0x1048, v7
	v_add_u32_e32 v38, 0x1050, v7
	ds_read2_b64 v[8:11], v6 offset1:1
	ds_read2_b64 v[12:15], v6 offset0:2 offset1:3
	ds_read2_b64 v[16:19], v6 offset0:4 offset1:5
	ds_read2_b64 v[20:23], v6 offset0:6 offset1:7
	ds_read2_b32 v[24:25], v7 offset1:1
	ds_read2_b32 v[26:27], v7 offset0:2 offset1:3
	ds_read2_b32 v[28:29], v7 offset0:4 offset1:5
	ds_read2_b32 v[30:31], v7 offset0:6 offset1:7
	v_add_u32_e32 v7, 0x1058, v7
	ds_read2_b32 v[34:35], v32 offset1:1
	ds_read2_b32 v[36:37], v36 offset1:1
	ds_read2_b32 v[38:39], v38 offset1:1
	ds_read2_b32 v[40:41], v7 offset1:1
	s_waitcnt lgkmcnt(7)
	v_mov_b32_e32 v42, v24
	s_waitcnt lgkmcnt(3)
	v_mov_b32_e32 v43, v34
	v_mov_b32_e32 v34, v25
	v_pk_mul_f32 v[8:9], v[42:43], v[8:9]
	v_mov_b32_e32 v24, v26
	s_waitcnt lgkmcnt(2)
	v_mov_b32_e32 v25, v36
	v_pk_mul_f32 v[10:11], v[34:35], v[10:11]
	v_sub_f32_e32 v7, v8, v9
	v_mov_b32_e32 v36, v27
	v_pk_mul_f32 v[12:13], v[24:25], v[12:13]
	v_sub_f32_e32 v8, v10, v11
	v_add_f32_e32 v3, v3, v7
	v_mov_b32_e32 v26, v28
	s_waitcnt lgkmcnt(1)
	v_mov_b32_e32 v27, v38
	v_pk_mul_f32 v[14:15], v[36:37], v[14:15]
	v_sub_f32_e32 v9, v12, v13
	v_add_f32_e32 v3, v3, v8
	v_mov_b32_e32 v38, v29
	v_pk_mul_f32 v[16:17], v[26:27], v[16:17]
	v_sub_f32_e32 v10, v14, v15
	v_add_f32_e32 v3, v3, v9
	v_mov_b32_e32 v28, v30
	s_waitcnt lgkmcnt(0)
	v_mov_b32_e32 v29, v40
	v_pk_mul_f32 v[18:19], v[38:39], v[18:19]
	v_sub_f32_e32 v11, v16, v17
	v_add_f32_e32 v3, v3, v10
	v_mov_b32_e32 v40, v31
	v_pk_mul_f32 v[20:21], v[28:29], v[20:21]
	v_sub_f32_e32 v12, v18, v19
	v_add_f32_e32 v3, v3, v11
	v_pk_mul_f32 v[22:23], v[40:41], v[22:23]
	v_sub_f32_e32 v13, v20, v21
	v_add_f32_e32 v3, v3, v12
	s_add_i32 s11, s11, 32
	v_sub_f32_e32 v14, v22, v23
	v_add_f32_e32 v3, v3, v13
	v_add_u32_e32 v6, 64, v6
	s_cmpk_eq_i32 s11, 0x100
	v_add_f32_e32 v3, v3, v14
	s_cbranch_scc0 .LBB0_629
	v_add_lshl_u32 v5, v0, s10, 2
	v_mov_b32_e32 v5, v116
	v_lshl_add_u32 v6, s6, 6, v1
	v_mul_f32_e32 v1, 0x3d372713, v3
	v_mul_f32_e32 v1, v3, v1
	v_fma_f32 v1, v3, v1, v3
	v_mul_f32_e32 v1, 0x3f4c422a, v1
	v_mul_f32_e32 v1, -2.0, v1
	v_mul_f32_e32 v1, 0x3fb8aa3b, v1
	v_exp_f32_e32 v9, v1
	v_lshlrev_b32_e32 v32, 1, v0
	v_or_b32_e32 v0, 8, v0
	v_ashrrev_i32_e32 v7, 31, v6
	ds_read_b32 v8, v4 offset:33312
	v_mul_u32_u24_e32 v4, 0x41, v0
	v_lshlrev_b64 v[0:1], 10, v[6:7]
	v_add_f32_e32 v6, 1.0, v9
	v_rcp_f32_e32 v6, v6
	s_lshl_b32 s6, s10, 1
	v_lshl_add_u64 v[0:1], s[4:5], 0, v[0:1]
	v_lshl_add_u64 v[0:1], v[0:1], 0, s[6:7]
	v_mul_f32_e32 v3, v3, v6
	v_bfe_u32 v6, v3, 16, 1
	v_lshl_add_u64 v[0:1], v[0:1], 0, v[32:33]
	v_add3_u32 v3, v3, v6, s28
	v_lshl_add_u32 v4, v4, 2, s21
	global_store_short_d16_hi v[0:1], v3, off
	s_mov_b32 s6, 0
	s_waitcnt vmcnt(1) lgkmcnt(0)
	v_mul_f32_e32 v3, v5, v8

; #define LAS __attribute__((address_space(3)))
; __device__ __forceinline__ float lane0(float v) { return __builtin_bit_cast(float, __builtin_amdgcn_readfirstlane(__builtin_bit_cast(int, v))); }
; __device__ __forceinline__ void attn_unit(const UnitDesc& u, LAS unsigned char* shm, float qkmax, float thresh) {
;     ...
;     const float ci = -Rown * LOG2E - qkmax;
;     const float kbq0 = Rq0 * LOG2E;
;     const int qabs = u.q0 + wid * 32 + r32;
;     float l_reg = 0.f; f32x16 o[2]; o[0] = f32x16{}; o[1] = f32x16{};
;     float lA = lfb[1], lB = lfb[2], lC = lfb[3];
;     { const float lf = lfb[0]; const float inc = inc4[0]; wsf[lane] = (inc - lf) * LOG2E; carry = lane0(inc);
;       *(LAS u32x4*)kdst = kreg; *(LAS u32x4*)vdst = vreg;
;       asm volatile("" : "+v"(qr[0]), "+v"(qr[1]), "+v"(qr[2]), "+v"(qr[3]));
;       asm volatile("s_waitcnt vmcnt(0)" : "+v"(kA), "+v"(vA), "+v"(kB), "+v"(vB), "+v"(kC), "+v"(vC) :: "memory"); }
;     int slot = 0, tile = NT - 1; bool stop = false;
.LBB0_772:
	v_lshlrev_b32_e32 v15, 1, v12
	s_lshl_b32 s12, s52, 10
	v_and_b32_e32 v15, 32, v15
	s_add_i32 s13, 0, 0x2000
	v_lshlrev_b32_e32 v142, 2, v136
	v_lshrrev_b32_e32 v12, 2, v12
	s_add_i32 s12, s12, 0
	v_add_u32_e32 v15, s13, v15
	v_and_or_b32 v12, v12, 3, v142
	s_lshl_b32 s13, s52, 9
	v_lshlrev_b32_e32 v12, 6, v12
	s_sub_i32 s53, s12, s13
	v_add_u32_e32 v147, s66, v10
	v_sub_f32_e32 v10, v0, v14
	v_lshl_add_u32 v143, v137, 4, s12
	v_add3_u32 v144, v15, v13, v12
	s_mov_b32 s12, 0xbfb8aa3b
	s_waitcnt lgkmcnt(0)
	v_mul_f32_e32 v146, 0x3fb8aa3b, v11
	v_mul_f32_e32 v10, 0x3fb8aa3b, v10
	v_lshl_add_u32 v11, v137, 2, s53
	v_mov_b32_e32 v14, v1
	v_mov_b32_e32 v15, v1
	v_lshlrev_b32_e32 v16, 10, v136
	v_lshlrev_b32_e32 v17, 4, v135
	v_fma_f32 v112, v21, s12, -v130
	v_mul_f32_e32 v197, 0x3fb8aa3b, v21
	s_mov_b64 s[98:99], 0
	s_nop 0
	v_readfirstlane_b32 s100, v197
	s_nop 3
	v_mov_b32_e32 v197, s100
	ds_write_b32 v11, v10 offset:32768
	v_readfirstlane_b32 s12, v0
	ds_write_b128 v143, v[2:5]
	ds_write_b128 v143, v[6:9] offset:8192
	v_mov_b32_e32 v0, v1
	v_mov_b32_e32 v2, v1
	v_mov_b32_e32 v3, v1
	v_mov_b32_e32 v4, v1
	v_mov_b32_e32 v5, v1
	v_mov_b32_e32 v6, v1
	v_mov_b32_e32 v7, v1
	v_mov_b32_e32 v8, v1
	v_mov_b32_e32 v9, v1
	v_mov_b32_e32 v10, v1
	v_mov_b32_e32 v11, v1
	v_mov_b32_e32 v12, v1
	v_mov_b32_e32 v13, v1
	v_mov_b64_e32 v[48:49], v[14:15]
	v_mov_b64_e32 v[64:65], v[14:15]
	v_mov_b64_e32 v[32:33], v[14:15]
	v_add3_u32 v145, 0, v16, v17
	s_add_i32 s73, s66, s49
	v_mov_b64_e32 v[46:47], v[12:13]
	v_mov_b64_e32 v[44:45], v[10:11]
	v_mov_b64_e32 v[42:43], v[8:9]
	v_mov_b64_e32 v[40:41], v[6:7]
	v_mov_b64_e32 v[38:39], v[4:5]
	v_mov_b64_e32 v[36:37], v[2:3]
	v_mov_b64_e32 v[34:35], v[0:1]
	v_mov_b64_e32 v[62:63], v[12:13]
	v_mov_b64_e32 v[60:61], v[10:11]
	v_mov_b64_e32 v[58:59], v[8:9]
	v_mov_b64_e32 v[56:57], v[6:7]
	v_mov_b64_e32 v[54:55], v[4:5]
	v_mov_b64_e32 v[52:53], v[2:3]
	v_mov_b64_e32 v[50:51], v[0:1]
	v_mov_b64_e32 v[30:31], v[12:13]
	v_mov_b64_e32 v[28:29], v[10:11]
	v_mov_b64_e32 v[26:27], v[8:9]
	v_mov_b64_e32 v[24:25], v[6:7]
	v_mov_b64_e32 v[22:23], v[4:5]
	v_mov_b64_e32 v[20:21], v[2:3]
	v_mov_b64_e32 v[18:19], v[0:1]
	v_mov_b64_e32 v[16:17], v[14:15]
	s_sub_i32 s72, s67, s28
	s_add_i32 s73, s73, 31
	v_mov_b32_e32 v113, v112
	v_mov_b32_e32 v114, v112
	v_mov_b32_e32 v115, v112
	v_mov_b32_e32 v116, v112
	v_mov_b32_e32 v117, v112
	v_mov_b32_e32 v118, v112
	v_mov_b32_e32 v119, v112
	v_mov_b32_e32 v120, v112
	v_mov_b32_e32 v121, v112
	v_mov_b32_e32 v122, v112
	v_mov_b32_e32 v123, v112
	v_mov_b32_e32 v124, v112
	v_mov_b32_e32 v125, v112
	v_mov_b32_e32 v126, v112
	v_mov_b32_e32 v127, v112
	s_lshl_b32 s75, s67, 6
	s_mov_b32 s70, 0
	v_mov_b32_e32 v148, 0
	s_mov_b64 s[62:63], 0
	v_mov_b32_e32 v150, s12
	v_mov_b64_e32 v[14:15], v[12:13]
	v_mov_b64_e32 v[12:13], v[10:11]
	v_mov_b64_e32 v[10:11], v[8:9]
	v_mov_b64_e32 v[8:9], v[6:7]
	v_mov_b64_e32 v[6:7], v[4:5]
	v_mov_b64_e32 v[4:5], v[2:3]
	v_mov_b64_e32 v[2:3], v[0:1]
	s_waitcnt vmcnt(0)
	s_branch .LBB0_777

; #define LAS __attribute__((address_space(3)))
; __device__ __forceinline__ unsigned pk2(float lo, float hi) { typedef __bf16 bf16x2_t_ __attribute__((ext_vector_type(2))); f32x2 v = {lo, hi}; return __builtin_bit_cast(unsigned, __builtin_convertvector(v, bf16x2_t_)); }
; __device__ __forceinline__ float sigmoidf_(float x) { return __builtin_amdgcn_rcpf(1.f + __expf(-x)); }
; __global__ void __launch_bounds__(NTHR, 2) hymba_fwd(Params P) {
;     ...
;         if (tid < 256) { const int row = tid >> 3, ch = tid & 7, col = 64 * ns + 8 * ch, m = PT + 32 * mb + row;
;             const f32x4 c0 = *(const LAS f32x4*)(Cs + row * ldc + 8 * ch) + *(const f32x4*)(P.b_glu + col), c1 = *(const LAS f32x4*)(Cs + row * ldc + 8 * ch + 4) + *(const f32x4*)(P.b_glu + col + 4);
;             const u32x4 ys = *(const u32x4*)(YSS + (size_t)(m - PT) * 512 + col), zs = *(const u32x4*)(ZS + (size_t)m * 512 + col);
;             u32x4 w;
;             w.x = pk2(bflo(ys.x) * sigmoidf_(c0[0]) * bflo(zs.x), bfhi(ys.x) * sigmoidf_(c0[1]) * bfhi(zs.x));
;             w.y = pk2(bflo(ys.y) * sigmoidf_(c0[2]) * bflo(zs.y), bfhi(ys.y) * sigmoidf_(c0[3]) * bfhi(zs.y));
;             w.z = pk2(bflo(ys.z) * sigmoidf_(c1[0]) * bflo(zs.z), bfhi(ys.z) * sigmoidf_(c1[1]) * bfhi(zs.z));
;             w.w = pk2(bflo(ys.w) * sigmoidf_(c1[2]) * bflo(zs.w), bfhi(ys.w) * sigmoidf_(c1[3]) * bfhi(zs.w));
;             *(u32x4*)(MX + (size_t)m * 1024 + col) = w; }
.Lmy_sk4_done:
.LBB0_693:
	v_mov_b32_e32 v0, v208
	s_waitcnt lgkmcnt(0)
	s_barrier
	s_nop 0
	v_cmp_gt_i32_e32 vcc, s17, v0
	s_and_saveexec_b64 s[62:63], vcc
	s_cbranch_execz .LBB0_687
	v_ashrrev_i32_e32 v1, 3, v0
	v_lshlrev_b32_e32 v0, 3, v0
	v_and_b32_e32 v0, 56, v0
	v_lshl_or_b32 v4, s50, 6, v0
	s_movk_i32 s50, 0x110
	v_add_u32_e32 v2, s51, v1
	v_mul_lo_u32 v1, v1, s50
	v_lshlrev_b32_e32 v0, 2, v0
	v_add3_u32 v5, 0, v1, v0
	v_add_u32_e32 v6, 0x10000, v2
	v_mov_b32_e32 v24, v6
	v_ashrrev_i32_e32 v25, 31, v6
	v_lshlrev_b64 v[24:25], 10, v[24:25]
	v_mov_b32_e32 v26, v4
	v_ashrrev_i32_e32 v27, 31, v4
	v_lshlrev_b64 v[26:27], 1, v[26:27]
	v_lshl_add_u64 v[28:29], s[4:5], 0, v[24:25]
	v_lshl_add_u64 v[28:29], v[28:29], 0, v[26:27]
	v_add_co_u32_e32 v28, vcc, s20, v28
	s_nop 1
	v_addc_co_u32_e32 v29, vcc, -1, v29, vcc
	v_lshl_add_u64 v[30:31], s[18:19], 0, v[24:25]
	v_lshl_add_u64 v[30:31], v[30:31], 0, v[26:27]
	global_load_dwordx4 v[32:35], v[28:29], off
	global_load_dwordx4 v[36:39], v[30:31], off
	ds_read_b128 v[0:3], v5
	ds_read_b128 v[8:11], v5 offset:16
	v_ashrrev_i32_e32 v5, 31, v4
	v_lshl_add_u64 v[16:17], v[4:5], 2, s[86:87]
	global_load_dwordx4 v[12:15], v[16:17], off offset:16
	s_nop 0
	global_load_dwordx4 v[16:19], v[16:17], off
	v_ashrrev_i32_e32 v7, 31, v6
	v_lshlrev_b64 v[4:5], 1, v[4:5]
	s_waitcnt vmcnt(1) lgkmcnt(0)
	v_pk_add_f32 v[12:13], v[8:9], v[12:13]
	v_lshlrev_b64 v[8:9], 10, v[6:7]
	s_waitcnt vmcnt(0)
	v_pk_add_f32 v[16:17], v[0:1], v[16:17]
	v_lshl_add_u64 v[0:1], s[4:5], 0, v[8:9]
	v_lshl_add_u64 v[0:1], v[0:1], 0, v[4:5]
	v_add_co_u32_e32 v0, vcc, s20, v0
	v_lshl_add_u64 v[8:9], s[18:19], 0, v[8:9]
	s_nop 0
	v_addc_co_u32_e32 v1, vcc, -1, v1, vcc
	v_pk_add_f32 v[18:19], v[2:3], v[18:19]
	v_mov_b64_e32 v[0:1], v[32:33]
	v_mov_b64_e32 v[2:3], v[34:35]
	v_lshl_add_u64 v[8:9], v[8:9], 0, v[4:5]
	v_pk_add_f32 v[14:15], v[10:11], v[14:15]
	v_mov_b64_e32 v[8:9], v[36:37]
	v_mov_b64_e32 v[10:11], v[38:39]
	v_mul_f32_e32 v16, 0xbfb8aa3b, v16
	v_mul_f32_e32 v17, 0xbfb8aa3b, v17
	v_exp_f32_e32 v16, v16
	v_exp_f32_e32 v17, v17
	v_lshlrev_b64 v[6:7], 11, v[6:7]
	v_lshl_add_u64 v[6:7], s[40:41], 0, v[6:7]
	v_add_f32_e32 v16, 1.0, v16
	v_add_f32_e32 v17, 1.0, v17
	v_rcp_f32_e32 v16, v16
	v_rcp_f32_e32 v17, v17
	v_lshl_add_u64 v[4:5], v[6:7], 0, v[4:5]
	s_waitcnt vmcnt(1)
	v_lshlrev_b32_e32 v20, 16, v0
	v_and_b32_e32 v21, 0xffff0000, v0
	v_pk_mul_f32 v[16:17], v[16:17], v[20:21]
	s_waitcnt vmcnt(0)
	v_lshlrev_b32_e32 v20, 16, v8
	v_and_b32_e32 v21, 0xffff0000, v8
	v_mul_f32_e32 v8, 0xbfb8aa3b, v18
	v_exp_f32_e32 v8, v8
	v_pk_mul_f32 v[16:17], v[16:17], v[20:21]
	v_lshlrev_b32_e32 v18, 16, v1
	v_cvt_pk_bf16_f32 v0, v16, v17
	v_add_f32_e32 v8, 1.0, v8
	v_rcp_f32_e32 v16, v8
	v_mul_f32_e32 v8, 0xbfb8aa3b, v19
	v_exp_f32_e32 v8, v8
	v_and_b32_e32 v19, 0xffff0000, v1
	v_add_f32_e32 v8, 1.0, v8
	v_rcp_f32_e32 v17, v8
	v_lshlrev_b32_e32 v8, 16, v9
	v_and_b32_e32 v9, 0xffff0000, v9
	v_pk_mul_f32 v[16:17], v[16:17], v[18:19]
	s_nop 0
	v_pk_mul_f32 v[8:9], v[16:17], v[8:9]
	s_nop 0
	v_cvt_pk_bf16_f32 v1, v8, v9
	v_mul_f32_e32 v8, 0xbfb8aa3b, v12
	v_mul_f32_e32 v9, 0xbfb8aa3b, v13
	v_exp_f32_e32 v8, v8
	v_exp_f32_e32 v9, v9
	v_lshlrev_b32_e32 v12, 16, v2
	v_and_b32_e32 v13, 0xffff0000, v2
	v_add_f32_e32 v8, 1.0, v8
	v_add_f32_e32 v9, 1.0, v9
	v_rcp_f32_e32 v8, v8
	v_rcp_f32_e32 v9, v9
	s_nop 0
	v_pk_mul_f32 v[8:9], v[8:9], v[12:13]
	v_lshlrev_b32_e32 v12, 16, v10
	v_and_b32_e32 v13, 0xffff0000, v10
	v_pk_mul_f32 v[8:9], v[8:9], v[12:13]
	v_lshlrev_b32_e32 v12, 16, v3
	v_cvt_pk_bf16_f32 v2, v8, v9
	v_mul_f32_e32 v8, 0xbfb8aa3b, v14
	v_mul_f32_e32 v9, 0xbfb8aa3b, v15
	v_exp_f32_e32 v8, v8
	v_exp_f32_e32 v9, v9
	v_and_b32_e32 v13, 0xffff0000, v3
	v_lshlrev_b32_e32 v10, 16, v11
	v_add_f32_e32 v8, 1.0, v8
	v_add_f32_e32 v9, 1.0, v9
	v_rcp_f32_e32 v8, v8
	v_rcp_f32_e32 v9, v9
	v_and_b32_e32 v11, 0xffff0000, v11
	v_pk_mul_f32 v[8:9], v[8:9], v[12:13]
	s_nop 0
	v_pk_mul_f32 v[8:9], v[8:9], v[10:11]
	s_nop 0
	v_cvt_pk_bf16_f32 v3, v8, v9
	global_store_dwordx4 v[4:5], v[0:3], off
	s_branch .LBB0_687

; #define LAS __attribute__((address_space(3)))
; #define MOD WSP(float, WS_MOD)
; __global__ void __launch_bounds__(NTHR, 2) hymba_fwd(Params P) {
;     ...
;         if (tid < 256) { const int row = tid >> 3, ch = tid & 7, col = 64 * ns + 8 * ch, sidx = 32 * mb + row; const float* gt = MOD + (size_t)(8 + (sidx >> 6)) * 3072 + 2048 + col;
;             const float* xr = P.x_sample + (size_t)sidx * DM + col; float* yr = out + O_YS + (size_t)sidx * DM + col;
;             *(f32x4*)yr = *(const f32x4*)xr + *(const f32x4*)gt * *(const LAS f32x4*)(Cs + row * ldc + 8 * ch);
;             *(f32x4*)(yr + 4) = *(const f32x4*)(xr + 4) + *(const f32x4*)(gt + 4) * *(const LAS f32x4*)(Cs + row * ldc + 8 * ch + 4); }
.Lmy_sk5_done:
.LBB0_892:
	v_mov_b32_e32 v0, v208
	s_waitcnt lgkmcnt(0)
	s_barrier
	s_nop 0
	v_cmp_gt_i32_e32 vcc, s21, v0
	s_and_saveexec_b64 s[62:63], vcc
	s_cbranch_execz .LBB0_886
	v_ashrrev_i32_e32 v8, 3, v0
	v_lshlrev_b32_e32 v0, 3, v0
	v_add_u32_e32 v2, s64, v8
	v_and_b32_e32 v9, 56, v0
	v_ashrrev_i32_e32 v1, 6, v2
	v_lshl_or_b32 v0, s53, 6, v9
	v_add_u32_e32 v1, 8, v1
	v_mov_b64_e32 v[4:5], s[92:93]
	v_mad_i64_i32 v[4:5], s[64:65], v1, s50, v[4:5]
	v_ashrrev_i32_e32 v1, 31, v0
	v_lshlrev_b64 v[16:17], 2, v[0:1]
	v_ashrrev_i32_e32 v3, 31, v2
	v_lshl_add_u64 v[18:19], v[4:5], 0, v[16:17]
	v_lshlrev_b64 v[12:13], 12, v[2:3]
	v_lshl_add_u64 v[0:1], s[38:39], 0, v[12:13]
	v_add_co_u32_e32 v4, vcc, s51, v18
	v_lshl_add_u64 v[20:21], v[0:1], 0, v[16:17]
	s_nop 0
	v_addc_co_u32_e32 v5, vcc, 0, v19, vcc
	global_load_dwordx4 v[0:3], v[20:21], off
	v_mul_lo_u32 v8, v8, s17
	global_load_dwordx4 v[4:7], v[4:5], off
	v_lshl_add_u64 v[32:33], v[18:19], 0, s[60:61]
	global_load_dwordx4 v[24:27], v[20:21], off offset:16
	global_load_dwordx4 v[28:31], v[32:33], off offset:16
	v_lshlrev_b32_e32 v9, 2, v9
	v_add3_u32 v14, 0, v8, v9
	ds_read_b128 v[8:11], v14
	v_lshl_add_u64 v[22:23], s[0:1], 0, v[12:13]
	v_lshl_add_u64 v[16:17], v[22:23], 0, v[16:17]
	ds_read_b128 v[12:15], v14 offset:16
	v_lshl_add_u64 v[18:19], v[18:19], 0, s[60:61]
	s_waitcnt vmcnt(2) lgkmcnt(1)
	v_pk_fma_f32 v[2:3], v[6:7], v[10:11], v[2:3]
	v_pk_fma_f32 v[0:1], v[4:5], v[8:9], v[0:1]
	global_store_dwordx4 v[16:17], v[0:3], off
	s_waitcnt vmcnt(1) lgkmcnt(0)
	v_pk_fma_f32 v[26:27], v[30:31], v[14:15], v[26:27]
	v_pk_fma_f32 v[24:25], v[28:29], v[12:13], v[24:25]
	global_store_dwordx4 v[16:17], v[24:27], off offset:16
	s_branch .LBB0_886
